# phase C compressed branch: q rows of heads 1..3 touched at item start so the per-head loads hit the cache
# baseline (speedup 1.0000x reference)
; #define MFMA16(a, b, c) __builtin_amdgcn_mfma_f32_16x16x32_bf16((a), (b), (c), 0, 0, 0)
; DI int my_tid() { int t = threadIdx.x; asm volatile("" : "+v"(t)); return t; }
; DI void nsa_wave(const Params& p, int layer, int b, int g, int t0, unsigned char* lds, bf16_t* ybase) {
;   const int lane = my_tid() & 63, qi = lane & 15, quad = lane >> 4;
;   const int t = t0 + qi, cur = t0 >> 6;
;   const long tok = (long)b * SEQ + t;
;   const int bg = b * 2 + g;
;   u32x2* lo = (u32x2*)lds + (my_tid() >> 6) * 1024 + lane;
;   const float mf_c = p.mfix()[layer * 4 + 0], mf_s = p.mfix()[layer * 4 + 1], mf_w = p.mfix()[layer * 4 + 2];
;   const bool on_c = mf_c > 60.f, on_s = mf_s > 60.f, on_w = mf_w > 60.f;
;   const float SC = 0.125f * 1.44269504089f;
;   const bf16_t* Kc = p.kc() + (long)bg * 128 * 64;
;   const bf16_t* Vc = p.vct() + (long)bg * 64 * 128;
;   f32x4 ph[8];
; #pragma unroll
;   for (int kt = 0; kt < 8; ++kt) ph[kt] = (f32x4){0.f, 0.f, 0.f, 0.f};
; #pragma unroll 1
;   for (int hh = 0; hh < 4; ++hh) {
;     const bf16_t* qp0 = p.nq() + ((long)(b * 8 + g * 4 + hh) * SEQ + t) * 64 + quad * 8;
;     const bf16x8 q0 = ld8(qp0), q1 = ld8(qp0 + 32); const float gt = p.ngate()[tok * 32 + g * 4 + hh];
;     f32x4 sc[8];
;     float mx = on_c ? -1e30f : mf_c;
; #pragma unroll
;     for (int kt = 0; kt < 8; ++kt) {
;       const bf16_t* kp = Kc + (long)(kt * 16 + qi) * 64 + quad * 8;
;       sc[kt] = MFMA16(ld8(kp), q0, ((f32x4){0.f, 0.f, 0.f, 0.f}));
;       sc[kt] = MFMA16(ld8(kp + 32), q1, sc[kt]);
;       sc[kt] = sc[kt] * SC;
; DI void phaseC(const Params& p0, int layer, unsigned char* lds, bool probe) {
;     ...
;     const int qi5 = it >> 5, qt = qi5 < 8 ? 15 - qi5 : qi5 - 8, bg = it & 31;
;     nsa_wave(p, layer, bg >> 1, bg & 1, qt * 128 + (my_tid() >> 6) * 16, lds, probe ? p.dummy() : p.nz());
.LBB0_706:
	s_lshr_b32 s0, s27, 1
	v_writelane_b32 v255, s0, 17
	s_lshl_b32 s0, s27, 17
	s_and_b32 s36, s0, 0x3c0000
	s_lshl_b32 s0, s27, 13
	s_and_b32 s8, s0, 0x3c000
	s_mov_b64 s[42:43], 0
	s_add_u32 s40, s92, s42
	s_addc_u32 s41, s93, s43
	s_ashr_i32 s0, s27, 5
	s_sub_i32 s1, 15, s0
	s_add_i32 s9, s0, -8
	v_mov_b32_e32 v0, v210
	s_cmp_lt_i32 s0, 8
	s_cselect_b32 s9, s1, s9
	v_mov_b32_e32 v243, v210
	s_and_b32 s26, s27, 31
	v_readlane_b32 s0, v255, 15
	v_and_b32_e32 v6, 64, v228
	v_ashrrev_i32_e32 v0, 2, v0
	v_mov_b32_e32 v2, v210
	v_readlane_b32 s1, v255, 16
	s_add_u32 s0, s40, s0
	v_cndmask_b32_e64 v4, 0, 1, s[2:3]
	v_xor_b32_e32 v5, 16, v228
	v_add_u32_e32 v240, 64, v6
	v_bfe_u32 v241, v243, 4, 2
	v_and_b32_e32 v6, -16, v0
	s_addc_u32 s1, s41, s1
	v_mov_b32_e32 v3, 0x1f671000
	v_xor_b32_e32 v7, 32, v228
	v_lshlrev_b32_e32 v132, 4, v4
	v_lshlrev_b32_e32 v4, 13, v4
	v_and_b32_e32 v242, 15, v243
	v_cmp_lt_i32_e32 vcc, v5, v240
	v_lshlrev_b32_e32 v136, 6, v241
	v_lshl_add_u32 v244, s9, 7, v6
	global_load_dwordx3 v[154:156], v3, s[0:1] offset:256
	v_or_b32_e32 v130, s8, v4
	v_lshlrev_b32_e32 v2, 7, v2
	v_and_b32_e32 v239, 63, v243
	v_cndmask_b32_e32 v4, v228, v5, vcc
	v_cmp_lt_i32_e32 vcc, v7, v240
	v_add_u32_e32 v12, 0x14f, v136
	v_or_b32_e32 v160, v244, v242
	s_lshl_b32 s0, s26, 14
	v_cndmask_b32_e32 v5, v228, v7, vcc
	v_and_b32_e32 v7, 0xffffe000, v2
	v_lshlrev_b32_e32 v8, 3, v239
	s_add_u32 s0, s40, s0
	v_cmp_gt_i32_e64 s[58:59], v12, v160
	v_add_u32_e32 v12, 0x24f, v136
	v_mov_b32_e32 v135, v1
	v_and_b32_e32 v134, 48, v243
	v_lshlrev_b32_e32 v0, 3, v241
	v_lshlrev_b32_e32 v175, 2, v4
	v_lshlrev_b32_e32 v159, 2, v5
	v_add3_u32 v157, 32, v7, v8
	v_or_b32_e32 v4, 31, v136
	v_or_b32_e32 v5, 47, v136
	v_or_b32_e32 v7, 63, v136
	s_addc_u32 s1, s41, 0
	v_cmp_gt_i32_e64 s[68:69], v12, v160
	v_or_b32_e32 v12, 0x31f, v136
	v_mov_b32_e32 v3, v1
	v_lshlrev_b32_e32 v2, 7, v242
	v_add_u32_e32 v8, 0x4f, v136
	v_or_b32_e32 v9, 0x11f, v136
	v_or_b32_e32 v13, 0x21f, v136
	v_cmp_gt_i32_e64 s[44:45], v4, v160
	v_cmp_gt_i32_e64 s[46:47], v5, v160
	v_cmp_gt_i32_e64 s[48:49], v7, v160
	v_lshl_add_u64 v[4:5], s[0:1], 0, v[134:135]
	v_lshl_add_u64 v[6:7], s[0:1], 0, v[0:1]
	s_mov_b64 s[0:1], 0x1f5f0000
	v_cmp_gt_i32_e64 s[70:71], v12, v160
	v_or_b32_e32 v12, 0x32f, v136
	v_or_b32_e32 v10, 0x12f, v136
	v_or_b32_e32 v11, 0x13f, v136
	v_or_b32_e32 v14, 0x22f, v136
	v_or_b32_e32 v15, 0x23f, v136
	v_cmp_gt_i32_e64 s[50:51], v8, v160
	v_cmp_gt_i32_e64 s[52:53], v9, v160
	v_cmp_gt_i32_e64 s[60:61], v13, v160
	v_lshl_add_u64 v[8:9], v[6:7], 0, s[0:1]
	v_lshl_add_u64 v[30:31], v[4:5], 0, v[2:3]
	s_mov_b64 s[0:1], 0x1f570000
	v_cmp_gt_i32_e64 s[72:73], v12, v160
	v_lshlrev_b32_e32 v12, 8, v242
	v_mov_b32_e32 v13, v1
	v_cmp_gt_i32_e64 s[54:55], v10, v160
	v_cmp_gt_i32_e64 s[56:57], v11, v160
	v_cmp_gt_i32_e64 s[62:63], v14, v160
	v_lshl_add_u64 v[10:11], v[30:31], 0, s[0:1]
	v_cmp_gt_i32_e64 s[66:67], v15, v160
	v_lshl_add_u64 v[112:113], v[8:9], 0, v[12:13]
	v_or_b32_e32 v14, 0x1000, v12
	v_mov_b32_e32 v15, v1
	v_or_b32_e32 v16, 0x2000, v12
	v_mov_b32_e32 v17, v1
	v_or_b32_e32 v12, 0x3000, v12
	s_mov_b64 s[0:1], 0x1f5f0040
	v_lshl_add_u64 v[68:69], v[8:9], 0, v[14:15]
	v_lshl_add_u64 v[72:73], v[8:9], 0, v[16:17]
	v_lshl_add_u64 v[84:85], v[8:9], 0, v[12:13]
	v_lshl_add_u64 v[8:9], v[6:7], 0, s[0:1]
	s_mov_b64 s[0:1], 0x1f5f0080
	v_lshl_add_u64 v[88:89], v[8:9], 0, v[14:15]
	v_lshl_add_u64 v[92:93], v[8:9], 0, v[16:17]
	v_lshl_add_u64 v[96:97], v[8:9], 0, v[12:13]
	v_lshl_add_u64 v[8:9], v[6:7], 0, s[0:1]
	s_mov_b64 s[0:1], 0x1f5f00c0
	v_lshl_add_u64 v[6:7], v[6:7], 0, s[0:1]
	s_mov_b32 s0, 0x1f571000
	v_add_co_u32_e32 v38, vcc, s0, v30
	s_mov_b32 s0, 0x1f572000
	s_nop 0
	v_addc_co_u32_e32 v39, vcc, 0, v31, vcc
	v_add_co_u32_e32 v42, vcc, s0, v30
	s_mov_b32 s0, 0x1f573000
	s_nop 0
	v_addc_co_u32_e32 v43, vcc, 0, v31, vcc
	v_add_co_u32_e32 v62, vcc, s0, v30
	v_lshl_add_u64 v[100:101], v[8:9], 0, v[14:15]
	v_lshl_add_u64 v[104:105], v[8:9], 0, v[16:17]
	v_lshl_add_u64 v[116:117], v[8:9], 0, v[12:13]
	v_lshl_add_u64 v[120:121], v[6:7], 0, v[14:15]
	v_lshl_add_u64 v[124:125], v[6:7], 0, v[16:17]
	v_lshl_add_u64 v[128:129], v[6:7], 0, v[12:13]
	v_addc_co_u32_e32 v63, vcc, 0, v31, vcc
	global_load_dwordx4 v[2:5], v[10:11], off offset:64
	global_load_dwordx4 v[6:9], v[10:11], off offset:2048
	s_nop 0
	global_load_dwordx4 v[10:13], v[10:11], off offset:2112
	s_nop 0
	global_load_dwordx4 v[14:17], v[38:39], off
	global_load_dwordx4 v[18:21], v[38:39], off offset:64
	global_load_dwordx4 v[22:25], v[38:39], off offset:2048
	global_load_dwordx4 v[26:29], v[38:39], off offset:2112
	global_load_dwordx4 v[30:33], v[42:43], off offset:64
	global_load_dwordx4 v[34:37], v[42:43], off offset:2048
	s_nop 0
	global_load_dwordx4 v[38:41], v[38:39], off offset:-4096
	s_nop 0
	global_load_dwordx4 v[42:45], v[42:43], off offset:2112
	s_nop 0
	global_load_dwordx4 v[46:49], v[62:63], off offset:-4096
	global_load_dwordx4 v[50:53], v[62:63], off
	global_load_dwordx4 v[54:57], v[62:63], off offset:64
	global_load_dwordx4 v[58:61], v[62:63], off offset:2048
	s_nop 0
	global_load_dwordx4 v[62:65], v[62:63], off offset:2112
	s_nop 0
	global_load_dwordx2 v[66:67], v[68:69], off
	s_nop 0
	global_load_dwordx2 v[68:69], v[68:69], off offset:32
	s_nop 0
	global_load_dwordx2 v[70:71], v[72:73], off
	s_nop 0
	global_load_dwordx2 v[72:73], v[72:73], off offset:32
	s_nop 0
	global_load_dwordx2 v[74:75], v[112:113], off
	global_load_dwordx2 v[76:77], v[112:113], off offset:32
; DI void nsa_wave(const Params& p, int layer, int b, int g, int t0, unsigned char* lds, bf16_t* ybase) {
;     ...
;   const float mf_c = p.mfix()[layer * 4 + 0], mf_s = p.mfix()[layer * 4 + 1], mf_w = p.mfix()[layer * 4 + 2];
;   const bool on_c = mf_c > 60.f, on_s = mf_s > 60.f, on_w = mf_w > 60.f;
;   const float SC = 0.125f * 1.44269504089f;
;   const bf16_t* Kc = p.kc() + (long)bg * 128 * 64;
;   const bf16_t* Vc = p.vct() + (long)bg * 64 * 128;
;   f32x4 ph[8];
; #pragma unroll
;   for (int kt = 0; kt < 8; ++kt) ph[kt] = (f32x4){0.f, 0.f, 0.f, 0.f};
; #pragma unroll 1
;   for (int hh = 0; hh < 4; ++hh) {
;     const bf16_t* qp0 = p.nq() + ((long)(b * 8 + g * 4 + hh) * SEQ + t) * 64 + quad * 8;
;     const bf16x8 q0 = ld8(qp0), q1 = ld8(qp0 + 32); const float gt = p.ngate()[tok * 32 + g * 4 + hh];
	global_load_dwordx2 v[78:79], v[112:113], off offset:64
	global_load_dwordx2 v[80:81], v[112:113], off offset:96
	global_load_dwordx2 v[82:83], v[84:85], off
	s_nop 0
	global_load_dwordx2 v[84:85], v[84:85], off offset:32
	s_nop 0
	global_load_dwordx2 v[86:87], v[88:89], off
	s_nop 0
	global_load_dwordx2 v[88:89], v[88:89], off offset:32
	s_nop 0
	global_load_dwordx2 v[90:91], v[92:93], off
	s_nop 0
	global_load_dwordx2 v[92:93], v[92:93], off offset:32
	s_nop 0
	global_load_dwordx2 v[94:95], v[96:97], off
	s_nop 0
	global_load_dwordx2 v[96:97], v[96:97], off offset:32
	s_nop 0
	global_load_dwordx2 v[98:99], v[100:101], off
	s_nop 0
	global_load_dwordx2 v[100:101], v[100:101], off offset:32
	s_nop 0
	global_load_dwordx2 v[102:103], v[104:105], off
	s_nop 0
	global_load_dwordx2 v[104:105], v[104:105], off offset:32
	s_nop 0
	global_load_dwordx2 v[106:107], v[112:113], off offset:128
	global_load_dwordx2 v[108:109], v[112:113], off offset:160
	global_load_dwordx2 v[110:111], v[112:113], off offset:192
	s_nop 0
	global_load_dwordx2 v[112:113], v[112:113], off offset:224
	s_nop 0
	global_load_dwordx2 v[114:115], v[116:117], off
	s_nop 0
	global_load_dwordx2 v[116:117], v[116:117], off offset:32
	s_nop 0
	global_load_dwordx2 v[118:119], v[120:121], off
	s_nop 0
	global_load_dwordx2 v[120:121], v[120:121], off offset:32
	s_nop 0
	global_load_dwordx2 v[122:123], v[124:125], off
	s_nop 0
	global_load_dwordx2 v[124:125], v[124:125], off offset:32
	s_nop 0
	global_load_dwordx2 v[126:127], v[128:129], off
	s_nop 0
	global_load_dwordx2 v[128:129], v[128:129], off offset:32
	v_or_b32_e32 v135, 0x33f, v136
	v_cmp_gt_i32_e64 s[74:75], v135, v160
	v_add_u32_e32 v135, 0x34f, v136
	v_cmp_gt_i32_e64 s[76:77], v135, v160
	v_or_b32_e32 v135, 0x41f, v136
	v_cmp_gt_i32_e64 s[78:79], v135, v160
	v_or_b32_e32 v135, 0x42f, v136
	v_cmp_gt_i32_e64 s[80:81], v135, v160
	v_or_b32_e32 v135, 0x43f, v136
	v_cmp_gt_i32_e64 s[82:83], v135, v160
	v_add_u32_e32 v135, 0x44f, v136
	v_cmp_gt_i32_e64 s[84:85], v135, v160
	v_or_b32_e32 v135, 0x51f, v136
	v_cmp_gt_i32_e64 s[86:87], v135, v160
	v_or_b32_e32 v135, 0x52f, v136
	v_mov_b32_e32 v131, v1
	v_cmp_gt_i32_e64 s[4:5], v135, v160
	v_or_b32_e32 v135, 0x53f, v136
	v_ashrrev_i32_e32 v161, 31, v160
	v_readlane_b32 s0, v254, 51
	v_mov_b32_e32 v133, v1
	v_cmp_gt_i32_e64 s[38:39], v135, v160
	v_add_u32_e32 v135, 0x54f, v136
	v_readlane_b32 s1, v254, 52
	v_lshl_add_u64 v[130:131], v[160:161], 0, v[130:131]
	s_waitcnt vmcnt(48)
	v_cmp_nlt_f32_e64 s[64:65], s25, v154
	v_cmp_gt_i32_e64 s[24:25], v135, v160
	v_or_b32_e32 v135, 0x61f, v136
	v_add_u32_e32 v137, 0x74f, v136
	v_lshl_add_u64 v[132:133], s[0:1], 0, v[132:133]
	v_lshlrev_b64 v[130:131], 7, v[130:131]
	v_cmp_gt_i32_e64 s[28:29], v135, v160
	v_or_b32_e32 v135, 0x62f, v136
	v_cmp_eq_u32_e32 vcc, 3, v241
	v_cmp_gt_i32_e64 s[8:9], v137, v160
	v_or_b32_e32 v174, 0x63f, v136
	v_add_u32_e32 v176, 0x64f, v136
	v_or_b32_e32 v177, 0x71f, v136
	v_or_b32_e32 v178, 0x72f, v136
	v_or_b32_e32 v179, 0x73f, v136
	v_lshlrev_b64 v[136:137], 7, v[160:161]
	v_lshl_add_u64 v[132:133], v[132:133], 0, s[36:37]
	v_or_b32_e32 v130, v130, v134
	v_mov_b32_e32 v166, 0
	s_mov_b32 s30, 0
	v_lshlrev_b32_e32 v158, 2, v241
	s_or_b64 s[96:97], vcc, s[8:9]
	v_cmp_gt_i32_e64 s[8:9], v135, v160
	v_lshl_add_u64 v[170:171], v[132:133], 0, v[136:137]
	v_lshl_add_u64 v[172:173], s[92:93], 0, v[130:131]
	v_mov_b32_e32 v167, v166
	v_mov_b32_e32 v168, v166
	v_mov_b32_e32 v169, v166
	v_mov_b32_e32 v162, v166
	v_mov_b32_e32 v163, v166
	v_mov_b32_e32 v164, v166
	v_mov_b32_e32 v165, v166
	v_mov_b32_e32 v148, v166
	v_mov_b32_e32 v149, v166
	v_mov_b32_e32 v146, v166
	v_mov_b32_e32 v147, v166
	v_mov_b32_e32 v152, v166
	v_mov_b32_e32 v153, v166
	v_mov_b32_e32 v150, v166
	v_mov_b32_e32 v151, v166
	v_mov_b32_e32 v140, v166
	v_mov_b32_e32 v141, v166
	v_mov_b32_e32 v138, v166
	v_mov_b32_e32 v139, v166
	v_mov_b32_e32 v144, v166
	v_mov_b32_e32 v145, v166
	v_mov_b32_e32 v142, v166
	v_mov_b32_e32 v143, v166
	v_mov_b32_e32 v132, v166
	v_mov_b32_e32 v133, v166
	v_mov_b32_e32 v130, v166
	v_mov_b32_e32 v131, v166
	v_mov_b32_e32 v136, v166
	v_mov_b32_e32 v137, v166
	v_mov_b32_e32 v134, v166
	v_mov_b32_e32 v135, v166
	v_cmp_gt_i32_e64 s[10:11], v174, v160
	v_cmp_gt_i32_e64 s[12:13], v176, v160
	v_cmp_gt_i32_e64 s[14:15], v177, v160
	v_cmp_gt_i32_e64 s[16:17], v178, v160
	v_cmp_gt_i32_e64 s[18:19], v179, v160
	s_mov_b64 s[20:21], 0xe230000
	v_lshl_add_u64 v[222:223], v[172:173], 0, s[42:43]
	v_lshl_add_u64 v[222:223], v[222:223], 0, s[20:21]
	global_load_dwordx4 v[216:219], v[222:223], off
	global_load_dwordx4 v[246:249], v[222:223], off offset:64
	s_mov_b64 s[20:21], 0xe1f0000
	v_lshl_add_u64 v[222:223], v[172:173], 0, s[42:43]
	v_lshl_add_u64 v[222:223], v[222:223], 0, s[20:21]
	global_load_dwordx4 v[216:219], v[222:223], off
	global_load_dwordx4 v[246:249], v[222:223], off offset:64
	s_mov_b64 s[20:21], 0xe1b0000
	v_lshl_add_u64 v[222:223], v[172:173], 0, s[42:43]
	v_lshl_add_u64 v[222:223], v[222:223], 0, s[20:21]
	global_load_dwordx4 v[216:219], v[222:223], off
	global_load_dwordx4 v[246:249], v[222:223], off offset:64
	s_mov_b64 s[20:21], 0xe170000
	v_lshl_add_u64 v[222:223], v[172:173], 0, s[42:43]
	v_lshl_add_u64 v[222:223], v[222:223], 0, s[20:21]
	global_load_dwordx4 v[216:219], v[222:223], off
	global_load_dwordx4 v[246:249], v[222:223], off offset:64
	v_lshl_add_u64 v[222:223], v[170:171], 0, s[42:43]
	global_load_dword v220, v[222:223], off
	s_branch .LBB0_708
